# v75 + GEMM K loops (in-proj, FFN-in, three 128-row loops): per-MFMA-block s_setprio flips removed, one static s_setprio 1 for waves 4-7 before each loop
# speedup vs baseline: 1.0016x; 1.0013x over previous
.LBB0_46:
	s_andn2_b64 vcc, exec, s[48:49]
	v_mov_b32_e32 v7, 0
	s_cbranch_vccnz .LBB0_78
	s_and_b64 s[4:5], s[64:65], exec
	v_mov_b32_e32 v60, 0
	s_cselect_b32 s9, s91, s42
	s_cselect_b32 s43, s92, s68
	s_mov_b32 s67, 0
	s_movk_i32 s69, 0x100
	v_mov_b32_e32 v61, v60
	v_mov_b32_e32 v62, v60
	v_mov_b32_e32 v63, v60
	v_mov_b32_e32 v64, v60
	v_mov_b32_e32 v65, v60
	v_mov_b32_e32 v66, v60
	v_mov_b32_e32 v67, v60
	v_mov_b32_e32 v56, v60
	v_mov_b32_e32 v57, v60
	v_mov_b32_e32 v58, v60
	v_mov_b32_e32 v59, v60
	v_mov_b32_e32 v52, v60
	v_mov_b32_e32 v53, v60
	v_mov_b32_e32 v54, v60
	v_mov_b32_e32 v55, v60
	v_mov_b32_e32 v48, v60
	v_mov_b32_e32 v49, v60
	v_mov_b32_e32 v50, v60
	v_mov_b32_e32 v51, v60
	v_mov_b32_e32 v44, v60
	v_mov_b32_e32 v45, v60
	v_mov_b32_e32 v46, v60
	v_mov_b32_e32 v47, v60
	v_mov_b32_e32 v40, v60
	v_mov_b32_e32 v41, v60
	v_mov_b32_e32 v42, v60
	v_mov_b32_e32 v43, v60
	v_mov_b32_e32 v36, v60
	v_mov_b32_e32 v37, v60
	v_mov_b32_e32 v38, v60
	v_mov_b32_e32 v39, v60
	v_mov_b32_e32 v32, v60
	v_mov_b32_e32 v33, v60
	v_mov_b32_e32 v34, v60
	v_mov_b32_e32 v35, v60
	v_mov_b32_e32 v28, v60
	v_mov_b32_e32 v29, v60
	v_mov_b32_e32 v30, v60
	v_mov_b32_e32 v31, v60
	v_mov_b32_e32 v24, v60
	v_mov_b32_e32 v25, v60
	v_mov_b32_e32 v26, v60
	v_mov_b32_e32 v27, v60
	v_mov_b32_e32 v20, v60
	v_mov_b32_e32 v21, v60
	v_mov_b32_e32 v22, v60
	v_mov_b32_e32 v23, v60
	v_mov_b32_e32 v16, v60
	v_mov_b32_e32 v17, v60
	v_mov_b32_e32 v18, v60
	v_mov_b32_e32 v19, v60
	v_mov_b32_e32 v12, v60
	v_mov_b32_e32 v13, v60
	v_mov_b32_e32 v14, v60
	v_mov_b32_e32 v15, v60
	v_mov_b32_e32 v8, v60
	v_mov_b32_e32 v9, v60
	v_mov_b32_e32 v10, v60
	v_mov_b32_e32 v11, v60
	v_mov_b32_e32 v4, v60
	v_mov_b32_e32 v5, v60
	v_mov_b32_e32 v6, v60
	v_mov_b32_e32 v7, v60
	v_readfirstlane_b32 vcc_lo, v202
	s_nop 3
	s_lshr_b32 vcc_lo, vcc_lo, 8
	s_cmp_lg_u32 vcc_lo, 0
	s_cbranch_scc0 .Lprio_skip0
	s_setprio 1
.Lprio_skip0:
.LBB0_48:
	s_add_i32 s4, s67, 2
	s_cmp_lt_i32 s4, s79
	s_cselect_b32 s4, 0, s79
	s_cselect_b32 s5, s42, s9
	s_cselect_b32 s20, s68, s43
	s_lshl_b32 s70, s4, 7
	s_sub_i32 s4, s5, s70
	s_sub_i32 s5, s20, s70
	s_add_i32 s20, s69, s5
	s_mul_i32 s5, s82, 0xc000
	s_add_i32 s70, s5, 0xffff4000
	s_add_i32 s5, s5, 0
	v_add_u32_e32 v0, s5, v162
	v_add_u32_e32 v1, s5, v163
	ds_read_b128 v[68:71], v0
	ds_read_b128 v[72:75], v1
	ds_read_b128 v[76:79], v0 offset:2048
	ds_read_b128 v[80:83], v1 offset:2048
	ds_read_b128 v[84:87], v0 offset:16384
	ds_read_b128 v[88:91], v1 offset:16384
	ds_read_b128 v[92:95], v0 offset:18432
	ds_read_b128 v[96:99], v1 offset:18432
	s_add_i32 s4, s69, s4
	s_cmp_lg_u32 s82, 0
	v_add_u32_e32 v0, s5, v160
	v_add_u32_e32 v1, s5, v161
	s_cselect_b32 s5, s70, 0x18000
	s_add_i32 s72, s78, s5
	v_lshl_add_u64 v[146:147], v[132:133], 0, s[20:21]
	s_mov_b32 m0, s72
	s_add_i32 s70, s20, s77
	s_mov_b32 s71, s21
	ds_read_b128 v[100:103], v0 offset:32768
	ds_read_b128 v[104:107], v0 offset:34816
	ds_read_b128 v[108:111], v1 offset:32768
	ds_read_b128 v[112:115], v1 offset:34816
	ds_read_b128 v[116:119], v0 offset:36864
	ds_read_b128 v[120:123], v0 offset:38912
	ds_read_b128 v[124:127], v1 offset:36864
	ds_read_b128 v[128:131], v1 offset:38912
	global_load_lds_dwordx4 v[146:147], off
	v_lshl_add_u64 v[146:147], v[132:133], 0, s[70:71]
	s_add_i32 m0, s72, 0x2000
	s_add_i32 s70, s20, s81
	global_load_lds_dwordx4 v[146:147], off
	s_add_i32 m0, s72, 0x4000
	v_lshl_add_u64 v[146:147], v[132:133], 0, s[70:71]
	s_add_i32 s20, s20, s87
	global_load_lds_dwordx4 v[146:147], off
	v_lshl_add_u64 v[146:147], v[132:133], 0, s[20:21]
	s_add_i32 m0, s72, 0x6000
	s_mov_b32 s5, s21
	global_load_lds_dwordx4 v[146:147], off
	s_add_i32 m0, s72, 0x8000
	v_lshl_add_u64 v[146:147], v[134:135], 0, s[4:5]
	s_add_i32 s20, s4, s76
	global_load_lds_dwordx4 v[146:147], off
	v_lshl_add_u64 v[146:147], v[134:135], 0, s[20:21]
	s_add_i32 m0, s72, 0xa000
	s_nop 0
	global_load_lds_dwordx4 v[146:147], off
	s_waitcnt vmcnt(6)
	s_waitcnt lgkmcnt(0)
	s_barrier
	s_waitcnt lgkmcnt(0)
	v_mfma_f32_16x16x32_bf16 v[60:63], v[68:71], v[100:103], v[60:63]
	v_mfma_f32_16x16x32_bf16 v[64:67], v[76:79], v[100:103], v[64:67]
	v_mfma_f32_16x16x32_bf16 v[56:59], v[68:71], v[104:107], v[56:59]
	v_mfma_f32_16x16x32_bf16 v[52:55], v[76:79], v[104:107], v[52:55]
	v_mfma_f32_16x16x32_bf16 v[48:51], v[68:71], v[116:119], v[48:51]
	v_mfma_f32_16x16x32_bf16 v[44:47], v[76:79], v[116:119], v[44:47]
	v_mfma_f32_16x16x32_bf16 v[40:43], v[68:71], v[120:123], v[40:43]
	v_mfma_f32_16x16x32_bf16 v[36:39], v[76:79], v[120:123], v[36:39]
	v_mfma_f32_16x16x32_bf16 v[60:63], v[72:75], v[108:111], v[60:63]
	v_mfma_f32_16x16x32_bf16 v[64:67], v[80:83], v[108:111], v[64:67]
	v_mfma_f32_16x16x32_bf16 v[56:59], v[72:75], v[112:115], v[56:59]
	v_mfma_f32_16x16x32_bf16 v[52:55], v[80:83], v[112:115], v[52:55]
	v_mfma_f32_16x16x32_bf16 v[48:51], v[72:75], v[124:127], v[48:51]
	v_mfma_f32_16x16x32_bf16 v[44:47], v[80:83], v[124:127], v[44:47]
	v_mfma_f32_16x16x32_bf16 v[40:43], v[72:75], v[128:131], v[40:43]
	v_mfma_f32_16x16x32_bf16 v[36:39], v[80:83], v[128:131], v[36:39]
	v_mfma_f32_16x16x32_bf16 v[32:35], v[84:87], v[100:103], v[32:35]
	v_mfma_f32_16x16x32_bf16 v[28:31], v[92:95], v[100:103], v[28:31]
	v_mfma_f32_16x16x32_bf16 v[24:27], v[84:87], v[104:107], v[24:27]
	v_mfma_f32_16x16x32_bf16 v[20:23], v[92:95], v[104:107], v[20:23]
	v_mfma_f32_16x16x32_bf16 v[16:19], v[84:87], v[116:119], v[16:19]
	v_mfma_f32_16x16x32_bf16 v[12:15], v[92:95], v[116:119], v[12:15]
	v_mfma_f32_16x16x32_bf16 v[8:11], v[84:87], v[120:123], v[8:11]
	v_mfma_f32_16x16x32_bf16 v[4:7], v[92:95], v[120:123], v[4:7]
	v_mfma_f32_16x16x32_bf16 v[32:35], v[88:91], v[108:111], v[32:35]
	v_mfma_f32_16x16x32_bf16 v[28:31], v[96:99], v[108:111], v[28:31]
	v_mfma_f32_16x16x32_bf16 v[24:27], v[88:91], v[112:115], v[24:27]
	v_mfma_f32_16x16x32_bf16 v[20:23], v[96:99], v[112:115], v[20:23]
	v_mfma_f32_16x16x32_bf16 v[16:19], v[88:91], v[124:127], v[16:19]
	v_mfma_f32_16x16x32_bf16 v[12:15], v[96:99], v[124:127], v[12:15]
	v_mfma_f32_16x16x32_bf16 v[8:11], v[88:91], v[128:131], v[8:11]
	v_mfma_f32_16x16x32_bf16 v[4:7], v[96:99], v[128:131], v[4:7]
	s_barrier
	s_add_i32 s4, s82, 1
	s_cmp_lg_u32 s82, 2
	s_cselect_b32 s82, s4, 0
	s_add_i32 s67, s67, 1
	s_addk_i32 s69, 0x80
	s_cmp_eq_u32 s79, s67
	s_cbranch_scc0 .LBB0_48
	s_setprio 0
	s_and_b64 vcc, exec, s[50:51]
	s_cbranch_vccz .LBB0_51

.LBB0_173:
	v_mov_b32_e32 v127, 0
	s_andn2_b64 vcc, exec, s[40:41]
	v_mov_b32_e32 v126, v127
	v_mov_b32_e32 v125, v127
	v_mov_b32_e32 v124, v127
	v_mov_b32_e32 v131, v127
	v_mov_b32_e32 v130, v127
	v_mov_b32_e32 v129, v127
	v_mov_b32_e32 v128, v127
	v_mov_b32_e32 v115, v127
	v_mov_b32_e32 v114, v127
	v_mov_b32_e32 v113, v127
	v_mov_b32_e32 v112, v127
	v_mov_b32_e32 v111, v127
	v_mov_b32_e32 v110, v127
	v_mov_b32_e32 v109, v127
	v_mov_b32_e32 v108, v127
	v_mov_b32_e32 v99, v127
	v_mov_b32_e32 v98, v127
	v_mov_b32_e32 v97, v127
	v_mov_b32_e32 v96, v127
	v_mov_b32_e32 v95, v127
	v_mov_b32_e32 v94, v127
	v_mov_b32_e32 v93, v127
	v_mov_b32_e32 v92, v127
	v_mov_b32_e32 v83, v127
	v_mov_b32_e32 v82, v127
	v_mov_b32_e32 v81, v127
	v_mov_b32_e32 v80, v127
	v_mov_b32_e32 v79, v127
	v_mov_b32_e32 v78, v127
	v_mov_b32_e32 v77, v127
	v_mov_b32_e32 v76, v127
	v_mov_b32_e32 v123, v127
	v_mov_b32_e32 v122, v127
	v_mov_b32_e32 v121, v127
	v_mov_b32_e32 v120, v127
	v_mov_b32_e32 v119, v127
	v_mov_b32_e32 v118, v127
	v_mov_b32_e32 v117, v127
	v_mov_b32_e32 v116, v127
	v_mov_b32_e32 v107, v127
	v_mov_b32_e32 v106, v127
	v_mov_b32_e32 v105, v127
	v_mov_b32_e32 v104, v127
	v_mov_b32_e32 v103, v127
	v_mov_b32_e32 v102, v127
	v_mov_b32_e32 v101, v127
	v_mov_b32_e32 v100, v127
	v_mov_b32_e32 v91, v127
	v_mov_b32_e32 v90, v127
	v_mov_b32_e32 v89, v127
	v_mov_b32_e32 v88, v127
	v_mov_b32_e32 v87, v127
	v_mov_b32_e32 v86, v127
	v_mov_b32_e32 v85, v127
	v_mov_b32_e32 v84, v127
	v_mov_b32_e32 v75, v127
	v_mov_b32_e32 v74, v127
	v_mov_b32_e32 v73, v127
	v_mov_b32_e32 v72, v127
	v_mov_b32_e32 v71, v127
	v_mov_b32_e32 v70, v127
	v_mov_b32_e32 v69, v127
	v_mov_b32_e32 v68, v127
	v_mov_b32_e32 v67, v127
	v_mov_b32_e32 v66, v127
	v_mov_b32_e32 v65, v127
	v_mov_b32_e32 v64, v127
	v_mov_b32_e32 v63, v127
	v_mov_b32_e32 v62, v127
	v_mov_b32_e32 v61, v127
	v_mov_b32_e32 v60, v127
	v_mov_b32_e32 v51, v127
	v_mov_b32_e32 v50, v127
	v_mov_b32_e32 v49, v127
	v_mov_b32_e32 v48, v127
	v_mov_b32_e32 v47, v127
	v_mov_b32_e32 v46, v127
	v_mov_b32_e32 v45, v127
	v_mov_b32_e32 v44, v127
	v_mov_b32_e32 v35, v127
	v_mov_b32_e32 v34, v127
	v_mov_b32_e32 v33, v127
	v_mov_b32_e32 v32, v127
	v_mov_b32_e32 v31, v127
	v_mov_b32_e32 v30, v127
	v_mov_b32_e32 v29, v127
	v_mov_b32_e32 v28, v127
	v_mov_b32_e32 v19, v127
	v_mov_b32_e32 v18, v127
	v_mov_b32_e32 v17, v127
	v_mov_b32_e32 v16, v127
	v_mov_b32_e32 v15, v127
	v_mov_b32_e32 v14, v127
	v_mov_b32_e32 v13, v127
	v_mov_b32_e32 v12, v127
	v_mov_b32_e32 v59, v127
	v_mov_b32_e32 v58, v127
	v_mov_b32_e32 v57, v127
	v_mov_b32_e32 v56, v127
	v_mov_b32_e32 v55, v127
	v_mov_b32_e32 v54, v127
	v_mov_b32_e32 v53, v127
	v_mov_b32_e32 v52, v127
	v_mov_b32_e32 v43, v127
	v_mov_b32_e32 v42, v127
	v_mov_b32_e32 v41, v127
	v_mov_b32_e32 v40, v127
	v_mov_b32_e32 v39, v127
	v_mov_b32_e32 v38, v127
	v_mov_b32_e32 v37, v127
	v_mov_b32_e32 v36, v127
	v_mov_b32_e32 v27, v127
	v_mov_b32_e32 v26, v127
	v_mov_b32_e32 v25, v127
	v_mov_b32_e32 v24, v127
	v_mov_b32_e32 v23, v127
	v_mov_b32_e32 v22, v127
	v_mov_b32_e32 v21, v127
	v_mov_b32_e32 v20, v127
	v_mov_b32_e32 v11, v127
	v_mov_b32_e32 v10, v127
	v_mov_b32_e32 v9, v127
	v_mov_b32_e32 v8, v127
	v_mov_b32_e32 v7, v127
	v_mov_b32_e32 v6, v127
	v_mov_b32_e32 v5, v127
	v_mov_b32_e32 v4, v127
	s_cbranch_vccnz .LBB0_176
	s_and_b64 s[48:49], s[44:45], exec
	v_mov_b32_e32 v4, 0
	s_cselect_b32 s73, s69, s46
	s_cselect_b32 s74, s70, s20
	s_add_i32 s75, s46, 0x80
	s_add_i32 s76, s20, 0x100
	s_mov_b32 s77, 0
	v_mov_b32_e32 v5, v4
	v_mov_b32_e32 v6, v4
	v_mov_b32_e32 v7, v4
	v_mov_b32_e32 v8, v4
	v_mov_b32_e32 v9, v4
	v_mov_b32_e32 v10, v4
	v_mov_b32_e32 v11, v4
	v_mov_b32_e32 v20, v4
	v_mov_b32_e32 v21, v4
	v_mov_b32_e32 v22, v4
	v_mov_b32_e32 v23, v4
	v_mov_b32_e32 v24, v4
	v_mov_b32_e32 v25, v4
	v_mov_b32_e32 v26, v4
	v_mov_b32_e32 v27, v4
	v_mov_b32_e32 v36, v4
	v_mov_b32_e32 v37, v4
	v_mov_b32_e32 v38, v4
	v_mov_b32_e32 v39, v4
	v_mov_b32_e32 v40, v4
	v_mov_b32_e32 v41, v4
	v_mov_b32_e32 v42, v4
	v_mov_b32_e32 v43, v4
	v_mov_b32_e32 v52, v4
	v_mov_b32_e32 v53, v4
	v_mov_b32_e32 v54, v4
	v_mov_b32_e32 v55, v4
	v_mov_b32_e32 v56, v4
	v_mov_b32_e32 v57, v4
	v_mov_b32_e32 v58, v4
	v_mov_b32_e32 v59, v4
	v_mov_b32_e32 v12, v4
	v_mov_b32_e32 v13, v4
	v_mov_b32_e32 v14, v4
	v_mov_b32_e32 v15, v4
	v_mov_b32_e32 v16, v4
	v_mov_b32_e32 v17, v4
	v_mov_b32_e32 v18, v4
	v_mov_b32_e32 v19, v4
	v_mov_b32_e32 v28, v4
	v_mov_b32_e32 v29, v4
	v_mov_b32_e32 v30, v4
	v_mov_b32_e32 v31, v4
	v_mov_b32_e32 v32, v4
	v_mov_b32_e32 v33, v4
	v_mov_b32_e32 v34, v4
	v_mov_b32_e32 v35, v4
	v_mov_b32_e32 v44, v4
	v_mov_b32_e32 v45, v4
	v_mov_b32_e32 v46, v4
	v_mov_b32_e32 v47, v4
	v_mov_b32_e32 v48, v4
	v_mov_b32_e32 v49, v4
	v_mov_b32_e32 v50, v4
	v_mov_b32_e32 v51, v4
	v_mov_b32_e32 v60, v4
	v_mov_b32_e32 v61, v4
	v_mov_b32_e32 v62, v4
	v_mov_b32_e32 v63, v4
	v_mov_b32_e32 v64, v4
	v_mov_b32_e32 v65, v4
	v_mov_b32_e32 v66, v4
	v_mov_b32_e32 v67, v4
	v_mov_b32_e32 v68, v4
	v_mov_b32_e32 v69, v4
	v_mov_b32_e32 v70, v4
	v_mov_b32_e32 v71, v4
	v_mov_b32_e32 v72, v4
	v_mov_b32_e32 v73, v4
	v_mov_b32_e32 v74, v4
	v_mov_b32_e32 v75, v4
	v_mov_b32_e32 v84, v4
	v_mov_b32_e32 v85, v4
	v_mov_b32_e32 v86, v4
	v_mov_b32_e32 v87, v4
	v_mov_b32_e32 v88, v4
	v_mov_b32_e32 v89, v4
	v_mov_b32_e32 v90, v4
	v_mov_b32_e32 v91, v4
	v_mov_b32_e32 v100, v4
	v_mov_b32_e32 v101, v4
	v_mov_b32_e32 v102, v4
	v_mov_b32_e32 v103, v4
	v_mov_b32_e32 v104, v4
	v_mov_b32_e32 v105, v4
	v_mov_b32_e32 v106, v4
	v_mov_b32_e32 v107, v4
	v_mov_b32_e32 v116, v4
	v_mov_b32_e32 v117, v4
	v_mov_b32_e32 v118, v4
	v_mov_b32_e32 v119, v4
	v_mov_b32_e32 v120, v4
	v_mov_b32_e32 v121, v4
	v_mov_b32_e32 v122, v4
	v_mov_b32_e32 v123, v4
	v_mov_b32_e32 v76, v4
	v_mov_b32_e32 v77, v4
	v_mov_b32_e32 v78, v4
	v_mov_b32_e32 v79, v4
	v_mov_b32_e32 v80, v4
	v_mov_b32_e32 v81, v4
	v_mov_b32_e32 v82, v4
	v_mov_b32_e32 v83, v4
	v_mov_b32_e32 v92, v4
	v_mov_b32_e32 v93, v4
	v_mov_b32_e32 v94, v4
	v_mov_b32_e32 v95, v4
	v_mov_b32_e32 v96, v4
	v_mov_b32_e32 v97, v4
	v_mov_b32_e32 v98, v4
	v_mov_b32_e32 v99, v4
	v_mov_b32_e32 v108, v4
	v_mov_b32_e32 v109, v4
	v_mov_b32_e32 v110, v4
	v_mov_b32_e32 v111, v4
	v_mov_b32_e32 v112, v4
	v_mov_b32_e32 v113, v4
	v_mov_b32_e32 v114, v4
	v_mov_b32_e32 v115, v4
	v_mov_b32_e32 v128, v4
	v_mov_b32_e32 v129, v4
	v_mov_b32_e32 v130, v4
	v_mov_b32_e32 v131, v4
	v_mov_b32_e32 v124, v4
	v_mov_b32_e32 v125, v4
	v_mov_b32_e32 v126, v4
	v_mov_b32_e32 v127, v4
	v_readfirstlane_b32 vcc_lo, v202
	s_nop 3
	s_lshr_b32 vcc_lo, vcc_lo, 8
	s_cmp_lg_u32 vcc_lo, 0
	s_cbranch_scc0 .Lprio_skip1
	s_setprio 1
.Lprio_skip1:
.LBB0_175:
	s_add_i32 s20, s75, 0x80
	s_cmp_eq_u32 s63, s77
	s_cselect_b32 s50, s73, s20
	s_cselect_b32 s48, s74, s76
	s_add_i32 s47, 0, 0x10000
	v_add_u32_e32 v0, s47, v136
	v_add_u32_e32 v1, s47, v137
	ds_read_b128 v[142:145], v0
	ds_read_b128 v[146:149], v1
	v_add_u32_e32 v0, s35, v136
	s_add_i32 s51, 0, 0x14000
	v_add_u32_e32 v1, s35, v137
	ds_read_b128 v[150:153], v0
	ds_read_b128 v[154:157], v1
	v_add_u32_e32 v0, s51, v136
	v_add_u32_e32 v1, s51, v137
	ds_read_b128 v[158:161], v0
	ds_read_b128 v[162:165], v1
	v_add_u32_e32 v0, s12, v136
	v_add_u32_e32 v1, s12, v137
	ds_read_b128 v[166:169], v0
	ds_read_b128 v[170:173], v1
	s_add_i32 s46, s50, 0x80
	s_add_i32 s20, s60, s75
	v_lshl_add_u64 v[194:195], v[134:135], 0, s[20:21]
	s_add_i32 m0, s55, 0xc000
	s_add_i32 s20, s68, s75
	ds_read_b128 v[174:177], v139
	ds_read_b128 v[178:181], v139 offset:2048
	ds_read_b128 v[182:185], v140
	ds_read_b128 v[186:189], v140 offset:2048
	ds_read_b128 v[190:193], v139 offset:4096
	ds_read_b128 v[220:223], v139 offset:6144
	ds_read_b128 v[224:227], v140 offset:4096
	ds_read_b128 v[228:231], v140 offset:6144
	global_load_lds_dwordx4 v[194:195], off
	v_lshl_add_u64 v[194:195], v[134:135], 0, s[20:21]
	s_add_i32 m0, s55, 0xe000
	s_nop 0
	global_load_lds_dwordx4 v[194:195], off
	s_waitcnt vmcnt(8)
	s_waitcnt lgkmcnt(0)
	s_barrier
	s_waitcnt lgkmcnt(0)
	v_mfma_f32_16x16x32_bf16 v[124:127], v[142:145], v[174:177], v[124:127]
	v_mfma_f32_16x16x32_bf16 v[128:131], v[150:153], v[174:177], v[128:131]
	v_mfma_f32_16x16x32_bf16 v[112:115], v[142:145], v[178:181], v[112:115]
	v_mfma_f32_16x16x32_bf16 v[108:111], v[150:153], v[178:181], v[108:111]
	v_mfma_f32_16x16x32_bf16 v[96:99], v[142:145], v[190:193], v[96:99]
	v_mfma_f32_16x16x32_bf16 v[92:95], v[150:153], v[190:193], v[92:95]
	v_mfma_f32_16x16x32_bf16 v[80:83], v[142:145], v[220:223], v[80:83]
	v_mfma_f32_16x16x32_bf16 v[76:79], v[150:153], v[220:223], v[76:79]
	v_mfma_f32_16x16x32_bf16 v[124:127], v[146:149], v[182:185], v[124:127]
	v_mfma_f32_16x16x32_bf16 v[128:131], v[154:157], v[182:185], v[128:131]
	v_mfma_f32_16x16x32_bf16 v[112:115], v[146:149], v[186:189], v[112:115]
	v_mfma_f32_16x16x32_bf16 v[108:111], v[154:157], v[186:189], v[108:111]
	v_mfma_f32_16x16x32_bf16 v[96:99], v[146:149], v[224:227], v[96:99]
	v_mfma_f32_16x16x32_bf16 v[92:95], v[154:157], v[224:227], v[92:95]
	v_mfma_f32_16x16x32_bf16 v[80:83], v[146:149], v[228:231], v[80:83]
	v_mfma_f32_16x16x32_bf16 v[76:79], v[154:157], v[228:231], v[76:79]
	v_mfma_f32_16x16x32_bf16 v[120:123], v[158:161], v[174:177], v[120:123]
	v_mfma_f32_16x16x32_bf16 v[116:119], v[166:169], v[174:177], v[116:119]
	v_mfma_f32_16x16x32_bf16 v[104:107], v[158:161], v[178:181], v[104:107]
	v_mfma_f32_16x16x32_bf16 v[100:103], v[166:169], v[178:181], v[100:103]
	v_mfma_f32_16x16x32_bf16 v[88:91], v[158:161], v[190:193], v[88:91]
	v_mfma_f32_16x16x32_bf16 v[84:87], v[166:169], v[190:193], v[84:87]
	v_mfma_f32_16x16x32_bf16 v[72:75], v[158:161], v[220:223], v[72:75]
	v_mfma_f32_16x16x32_bf16 v[68:71], v[166:169], v[220:223], v[68:71]
	v_mfma_f32_16x16x32_bf16 v[120:123], v[162:165], v[182:185], v[120:123]
	v_mfma_f32_16x16x32_bf16 v[116:119], v[170:173], v[182:185], v[116:119]
	v_mfma_f32_16x16x32_bf16 v[104:107], v[162:165], v[186:189], v[104:107]
	v_mfma_f32_16x16x32_bf16 v[100:103], v[170:173], v[186:189], v[100:103]
	v_mfma_f32_16x16x32_bf16 v[88:91], v[162:165], v[224:227], v[88:91]
	v_mfma_f32_16x16x32_bf16 v[84:87], v[170:173], v[224:227], v[84:87]
	v_mfma_f32_16x16x32_bf16 v[72:75], v[162:165], v[228:231], v[72:75]
	v_mfma_f32_16x16x32_bf16 v[68:71], v[170:173], v[228:231], v[68:71]
	s_barrier
	s_mov_b32 s49, s21
	s_add_i32 s47, s47, s54
	v_lshl_add_u64 v[194:195], v[132:133], 0, s[48:49]
	s_mov_b32 m0, s47
	s_add_i32 s20, s48, s53
	ds_read_b128 v[174:177], v139 offset:16384
	ds_read_b128 v[178:181], v139 offset:18432
	ds_read_b128 v[182:185], v140 offset:16384
	ds_read_b128 v[186:189], v140 offset:18432
	ds_read_b128 v[190:193], v139 offset:20480
	ds_read_b128 v[220:223], v139 offset:22528
	ds_read_b128 v[224:227], v140 offset:20480
	ds_read_b128 v[228:231], v140 offset:22528
	global_load_lds_dwordx4 v[194:195], off
	v_lshl_add_u64 v[194:195], v[132:133], 0, s[20:21]
	s_add_i32 m0, s47, 0x2000
	s_add_i32 s20, s20, s53
	s_add_i32 s47, s51, s54
	global_load_lds_dwordx4 v[194:195], off
	v_lshl_add_u64 v[194:195], v[132:133], 0, s[20:21]
	s_mov_b32 m0, s47
	s_add_i32 s20, s20, s53
	global_load_lds_dwordx4 v[194:195], off
	v_lshl_add_u64 v[194:195], v[132:133], 0, s[20:21]
	s_add_i32 m0, s47, 0x2000
	s_mov_b32 s51, s21
	global_load_lds_dwordx4 v[194:195], off
	v_lshl_add_u64 v[194:195], v[134:135], 0, s[50:51]
	s_mov_b32 m0, s55
	s_add_i32 s20, s50, s52
	global_load_lds_dwordx4 v[194:195], off
	v_lshl_add_u64 v[194:195], v[134:135], 0, s[20:21]
	s_mov_b32 m0, s56
	s_nop 0
	global_load_lds_dwordx4 v[194:195], off
	s_waitcnt vmcnt(8)
	s_waitcnt lgkmcnt(0)
	s_barrier
	s_waitcnt lgkmcnt(0)
	v_mfma_f32_16x16x32_bf16 v[64:67], v[142:145], v[174:177], v[64:67]
	v_mfma_f32_16x16x32_bf16 v[60:63], v[150:153], v[174:177], v[60:63]
	v_mfma_f32_16x16x32_bf16 v[48:51], v[142:145], v[178:181], v[48:51]
	v_mfma_f32_16x16x32_bf16 v[44:47], v[150:153], v[178:181], v[44:47]
	v_mfma_f32_16x16x32_bf16 v[32:35], v[142:145], v[190:193], v[32:35]
	v_mfma_f32_16x16x32_bf16 v[28:31], v[150:153], v[190:193], v[28:31]
	v_mfma_f32_16x16x32_bf16 v[16:19], v[142:145], v[220:223], v[16:19]
	v_mfma_f32_16x16x32_bf16 v[12:15], v[150:153], v[220:223], v[12:15]
	v_mfma_f32_16x16x32_bf16 v[64:67], v[146:149], v[182:185], v[64:67]
	v_mfma_f32_16x16x32_bf16 v[60:63], v[154:157], v[182:185], v[60:63]
	v_mfma_f32_16x16x32_bf16 v[48:51], v[146:149], v[186:189], v[48:51]
	v_mfma_f32_16x16x32_bf16 v[44:47], v[154:157], v[186:189], v[44:47]
	v_mfma_f32_16x16x32_bf16 v[32:35], v[146:149], v[224:227], v[32:35]
	v_mfma_f32_16x16x32_bf16 v[28:31], v[154:157], v[224:227], v[28:31]
	v_mfma_f32_16x16x32_bf16 v[16:19], v[146:149], v[228:231], v[16:19]
	v_mfma_f32_16x16x32_bf16 v[12:15], v[154:157], v[228:231], v[12:15]
	v_mfma_f32_16x16x32_bf16 v[56:59], v[158:161], v[174:177], v[56:59]
	v_mfma_f32_16x16x32_bf16 v[52:55], v[166:169], v[174:177], v[52:55]
	v_mfma_f32_16x16x32_bf16 v[40:43], v[158:161], v[178:181], v[40:43]
	v_mfma_f32_16x16x32_bf16 v[36:39], v[166:169], v[178:181], v[36:39]
	v_mfma_f32_16x16x32_bf16 v[24:27], v[158:161], v[190:193], v[24:27]
	v_mfma_f32_16x16x32_bf16 v[20:23], v[166:169], v[190:193], v[20:23]
	v_mfma_f32_16x16x32_bf16 v[8:11], v[158:161], v[220:223], v[8:11]
	v_mfma_f32_16x16x32_bf16 v[4:7], v[166:169], v[220:223], v[4:7]
	v_mfma_f32_16x16x32_bf16 v[56:59], v[162:165], v[182:185], v[56:59]
	v_mfma_f32_16x16x32_bf16 v[52:55], v[170:173], v[182:185], v[52:55]
	v_mfma_f32_16x16x32_bf16 v[40:43], v[162:165], v[186:189], v[40:43]
	v_mfma_f32_16x16x32_bf16 v[36:39], v[170:173], v[186:189], v[36:39]
	v_mfma_f32_16x16x32_bf16 v[24:27], v[162:165], v[224:227], v[24:27]
	v_mfma_f32_16x16x32_bf16 v[20:23], v[170:173], v[224:227], v[20:23]
	v_mfma_f32_16x16x32_bf16 v[8:11], v[162:165], v[228:231], v[8:11]
	v_mfma_f32_16x16x32_bf16 v[4:7], v[170:173], v[228:231], v[4:7]
	s_barrier
	s_add_i32 s47, 0, 0x18000
	v_add_u32_e32 v0, s47, v136
	v_add_u32_e32 v1, s47, v137
	ds_read_b128 v[142:145], v0
	ds_read_b128 v[146:149], v1
	v_add_u32_e32 v0, s13, v136
	s_add_i32 s49, 0, 0x1c000
	v_add_u32_e32 v1, s13, v137
	ds_read_b128 v[150:153], v0
	ds_read_b128 v[154:157], v1
	v_add_u32_e32 v0, s49, v136
	v_add_u32_e32 v1, s49, v137
	ds_read_b128 v[158:161], v0
	ds_read_b128 v[162:165], v1
	v_add_u32_e32 v0, s14, v136
	v_add_u32_e32 v1, s14, v137
	ds_read_b128 v[166:169], v0
	ds_read_b128 v[170:173], v1
	s_add_i32 s20, s20, s52
	s_mov_b32 m0, s57
	v_lshl_add_u64 v[194:195], v[134:135], 0, s[20:21]
	s_add_i32 s20, s20, s52
	ds_read_b128 v[174:177], v139 offset:32768
	ds_read_b128 v[178:181], v139 offset:34816
	ds_read_b128 v[182:185], v140 offset:32768
	ds_read_b128 v[186:189], v140 offset:34816
	ds_read_b128 v[190:193], v139 offset:36864
	ds_read_b128 v[220:223], v139 offset:38912
	ds_read_b128 v[224:227], v140 offset:36864
	ds_read_b128 v[228:231], v140 offset:38912
	global_load_lds_dwordx4 v[194:195], off
	v_lshl_add_u64 v[194:195], v[134:135], 0, s[20:21]
	s_mov_b32 m0, s58
	s_nop 0
	global_load_lds_dwordx4 v[194:195], off
	s_waitcnt vmcnt(8)
	s_waitcnt lgkmcnt(0)
	s_barrier
	s_waitcnt lgkmcnt(0)
	v_mfma_f32_16x16x32_bf16 v[124:127], v[142:145], v[174:177], v[124:127]
	v_mfma_f32_16x16x32_bf16 v[128:131], v[150:153], v[174:177], v[128:131]
	v_mfma_f32_16x16x32_bf16 v[112:115], v[142:145], v[178:181], v[112:115]
	v_mfma_f32_16x16x32_bf16 v[108:111], v[150:153], v[178:181], v[108:111]
	v_mfma_f32_16x16x32_bf16 v[96:99], v[142:145], v[190:193], v[96:99]
	v_mfma_f32_16x16x32_bf16 v[92:95], v[150:153], v[190:193], v[92:95]
	v_mfma_f32_16x16x32_bf16 v[80:83], v[142:145], v[220:223], v[80:83]
	v_mfma_f32_16x16x32_bf16 v[76:79], v[150:153], v[220:223], v[76:79]
	v_mfma_f32_16x16x32_bf16 v[124:127], v[146:149], v[182:185], v[124:127]
	v_mfma_f32_16x16x32_bf16 v[128:131], v[154:157], v[182:185], v[128:131]
	v_mfma_f32_16x16x32_bf16 v[112:115], v[146:149], v[186:189], v[112:115]
	v_mfma_f32_16x16x32_bf16 v[108:111], v[154:157], v[186:189], v[108:111]
	v_mfma_f32_16x16x32_bf16 v[96:99], v[146:149], v[224:227], v[96:99]
	v_mfma_f32_16x16x32_bf16 v[92:95], v[154:157], v[224:227], v[92:95]
	v_mfma_f32_16x16x32_bf16 v[80:83], v[146:149], v[228:231], v[80:83]
	v_mfma_f32_16x16x32_bf16 v[76:79], v[154:157], v[228:231], v[76:79]
	v_mfma_f32_16x16x32_bf16 v[120:123], v[158:161], v[174:177], v[120:123]
	v_mfma_f32_16x16x32_bf16 v[116:119], v[166:169], v[174:177], v[116:119]
	v_mfma_f32_16x16x32_bf16 v[104:107], v[158:161], v[178:181], v[104:107]
	v_mfma_f32_16x16x32_bf16 v[100:103], v[166:169], v[178:181], v[100:103]
	v_mfma_f32_16x16x32_bf16 v[88:91], v[158:161], v[190:193], v[88:91]
	v_mfma_f32_16x16x32_bf16 v[84:87], v[166:169], v[190:193], v[84:87]
	v_mfma_f32_16x16x32_bf16 v[72:75], v[158:161], v[220:223], v[72:75]
	v_mfma_f32_16x16x32_bf16 v[68:71], v[166:169], v[220:223], v[68:71]
	v_mfma_f32_16x16x32_bf16 v[120:123], v[162:165], v[182:185], v[120:123]
	v_mfma_f32_16x16x32_bf16 v[116:119], v[170:173], v[182:185], v[116:119]
	v_mfma_f32_16x16x32_bf16 v[104:107], v[162:165], v[186:189], v[104:107]
	v_mfma_f32_16x16x32_bf16 v[100:103], v[170:173], v[186:189], v[100:103]
	v_mfma_f32_16x16x32_bf16 v[88:91], v[162:165], v[224:227], v[88:91]
	v_mfma_f32_16x16x32_bf16 v[84:87], v[170:173], v[224:227], v[84:87]
	v_mfma_f32_16x16x32_bf16 v[72:75], v[162:165], v[228:231], v[72:75]
	v_mfma_f32_16x16x32_bf16 v[68:71], v[170:173], v[228:231], v[68:71]
	s_barrier
	s_add_i32 s20, s48, 0x80
	s_add_i32 s47, s47, s54
	v_lshl_add_u64 v[194:195], v[132:133], 0, s[20:21]
	s_mov_b32 m0, s47
	s_add_i32 s20, s20, s53
	ds_read_b128 v[174:177], v139 offset:49152
	ds_read_b128 v[178:181], v139 offset:51200
	ds_read_b128 v[182:185], v140 offset:49152
	ds_read_b128 v[186:189], v140 offset:51200
	ds_read_b128 v[190:193], v139 offset:53248
	ds_read_b128 v[220:223], v139 offset:55296
	ds_read_b128 v[224:227], v140 offset:53248
	ds_read_b128 v[228:231], v140 offset:55296
	global_load_lds_dwordx4 v[194:195], off
	v_lshl_add_u64 v[194:195], v[132:133], 0, s[20:21]
	s_add_i32 m0, s47, 0x2000
	s_add_i32 s20, s20, s53
	s_add_i32 s47, s49, s54
	global_load_lds_dwordx4 v[194:195], off
	v_lshl_add_u64 v[194:195], v[132:133], 0, s[20:21]
	s_mov_b32 m0, s47
	s_add_i32 s20, s20, s53
	global_load_lds_dwordx4 v[194:195], off
	v_lshl_add_u64 v[194:195], v[132:133], 0, s[20:21]
	s_add_i32 m0, s47, 0x2000
	s_mov_b32 s47, s21
	global_load_lds_dwordx4 v[194:195], off
	v_lshl_add_u64 v[194:195], v[134:135], 0, s[46:47]
	s_mov_b32 m0, s61
	s_add_i32 s20, s46, s52
	global_load_lds_dwordx4 v[194:195], off
	v_lshl_add_u64 v[194:195], v[134:135], 0, s[20:21]
	s_mov_b32 m0, s62
	s_nop 0
	global_load_lds_dwordx4 v[194:195], off
	s_waitcnt vmcnt(8)
	s_waitcnt lgkmcnt(0)
	s_barrier
	s_waitcnt lgkmcnt(0)
	v_mfma_f32_16x16x32_bf16 v[64:67], v[142:145], v[174:177], v[64:67]
	v_mfma_f32_16x16x32_bf16 v[60:63], v[150:153], v[174:177], v[60:63]
	v_mfma_f32_16x16x32_bf16 v[48:51], v[142:145], v[178:181], v[48:51]
	v_mfma_f32_16x16x32_bf16 v[44:47], v[150:153], v[178:181], v[44:47]
	v_mfma_f32_16x16x32_bf16 v[32:35], v[142:145], v[190:193], v[32:35]
	v_mfma_f32_16x16x32_bf16 v[28:31], v[150:153], v[190:193], v[28:31]
	v_mfma_f32_16x16x32_bf16 v[16:19], v[142:145], v[220:223], v[16:19]
	v_mfma_f32_16x16x32_bf16 v[12:15], v[150:153], v[220:223], v[12:15]
	v_mfma_f32_16x16x32_bf16 v[64:67], v[146:149], v[182:185], v[64:67]
	v_mfma_f32_16x16x32_bf16 v[60:63], v[154:157], v[182:185], v[60:63]
	v_mfma_f32_16x16x32_bf16 v[48:51], v[146:149], v[186:189], v[48:51]
	v_mfma_f32_16x16x32_bf16 v[44:47], v[154:157], v[186:189], v[44:47]
	v_mfma_f32_16x16x32_bf16 v[32:35], v[146:149], v[224:227], v[32:35]
	v_mfma_f32_16x16x32_bf16 v[28:31], v[154:157], v[224:227], v[28:31]
	v_mfma_f32_16x16x32_bf16 v[16:19], v[146:149], v[228:231], v[16:19]
	v_mfma_f32_16x16x32_bf16 v[12:15], v[154:157], v[228:231], v[12:15]
	v_mfma_f32_16x16x32_bf16 v[56:59], v[158:161], v[174:177], v[56:59]
	v_mfma_f32_16x16x32_bf16 v[52:55], v[166:169], v[174:177], v[52:55]
	v_mfma_f32_16x16x32_bf16 v[40:43], v[158:161], v[178:181], v[40:43]
	v_mfma_f32_16x16x32_bf16 v[36:39], v[166:169], v[178:181], v[36:39]
	v_mfma_f32_16x16x32_bf16 v[24:27], v[158:161], v[190:193], v[24:27]
	v_mfma_f32_16x16x32_bf16 v[20:23], v[166:169], v[190:193], v[20:23]
	v_mfma_f32_16x16x32_bf16 v[8:11], v[158:161], v[220:223], v[8:11]
	v_mfma_f32_16x16x32_bf16 v[4:7], v[166:169], v[220:223], v[4:7]
	v_mfma_f32_16x16x32_bf16 v[56:59], v[162:165], v[182:185], v[56:59]
	v_mfma_f32_16x16x32_bf16 v[52:55], v[170:173], v[182:185], v[52:55]
	v_mfma_f32_16x16x32_bf16 v[40:43], v[162:165], v[186:189], v[40:43]
	v_mfma_f32_16x16x32_bf16 v[36:39], v[170:173], v[186:189], v[36:39]
	v_mfma_f32_16x16x32_bf16 v[24:27], v[162:165], v[224:227], v[24:27]
	v_mfma_f32_16x16x32_bf16 v[20:23], v[170:173], v[224:227], v[20:23]
	v_mfma_f32_16x16x32_bf16 v[8:11], v[162:165], v[228:231], v[8:11]
	v_mfma_f32_16x16x32_bf16 v[4:7], v[170:173], v[228:231], v[4:7]
	s_barrier
	s_add_i32 s77, s77, 2
	s_addk_i32 s75, 0x100
	s_addk_i32 s76, 0x100
	s_cmp_ge_i32 s77, s59
	s_cbranch_scc0 .LBB0_175
	s_setprio 0

.LBB0_414:
	v_mov_b32_e32 v7, 0
	s_andn2_b64 vcc, exec, s[50:51]
	s_cbranch_vccnz .LBB0_462
	s_and_b64 s[4:5], s[68:69], exec
	v_mov_b32_e32 v64, 0
	s_cselect_b32 s9, s95, s42
	s_cselect_b32 s43, s96, s72
	s_mov_b32 s71, 0
	s_movk_i32 s73, 0x100
	v_mov_b32_e32 v65, v64
	v_mov_b32_e32 v66, v64
	v_mov_b32_e32 v67, v64
	v_mov_b32_e32 v60, v64
	v_mov_b32_e32 v61, v64
	v_mov_b32_e32 v62, v64
	v_mov_b32_e32 v63, v64
	v_mov_b32_e32 v56, v64
	v_mov_b32_e32 v57, v64
	v_mov_b32_e32 v58, v64
	v_mov_b32_e32 v59, v64
	v_mov_b32_e32 v52, v64
	v_mov_b32_e32 v53, v64
	v_mov_b32_e32 v54, v64
	v_mov_b32_e32 v55, v64
	v_mov_b32_e32 v48, v64
	v_mov_b32_e32 v49, v64
	v_mov_b32_e32 v50, v64
	v_mov_b32_e32 v51, v64
	v_mov_b32_e32 v44, v64
	v_mov_b32_e32 v45, v64
	v_mov_b32_e32 v46, v64
	v_mov_b32_e32 v47, v64
	v_mov_b32_e32 v40, v64
	v_mov_b32_e32 v41, v64
	v_mov_b32_e32 v42, v64
	v_mov_b32_e32 v43, v64
	v_mov_b32_e32 v36, v64
	v_mov_b32_e32 v37, v64
	v_mov_b32_e32 v38, v64
	v_mov_b32_e32 v39, v64
	v_mov_b32_e32 v32, v64
	v_mov_b32_e32 v33, v64
	v_mov_b32_e32 v34, v64
	v_mov_b32_e32 v35, v64
	v_mov_b32_e32 v28, v64
	v_mov_b32_e32 v29, v64
	v_mov_b32_e32 v30, v64
	v_mov_b32_e32 v31, v64
	v_mov_b32_e32 v24, v64
	v_mov_b32_e32 v25, v64
	v_mov_b32_e32 v26, v64
	v_mov_b32_e32 v27, v64
	v_mov_b32_e32 v20, v64
	v_mov_b32_e32 v21, v64
	v_mov_b32_e32 v22, v64
	v_mov_b32_e32 v23, v64
	v_mov_b32_e32 v16, v64
	v_mov_b32_e32 v17, v64
	v_mov_b32_e32 v18, v64
	v_mov_b32_e32 v19, v64
	v_mov_b32_e32 v12, v64
	v_mov_b32_e32 v13, v64
	v_mov_b32_e32 v14, v64
	v_mov_b32_e32 v15, v64
	v_mov_b32_e32 v8, v64
	v_mov_b32_e32 v9, v64
	v_mov_b32_e32 v10, v64
	v_mov_b32_e32 v11, v64
	v_mov_b32_e32 v4, v64
	v_mov_b32_e32 v5, v64
	v_mov_b32_e32 v6, v64
	v_mov_b32_e32 v7, v64
	v_readfirstlane_b32 vcc_lo, v202
	s_nop 3
	s_lshr_b32 vcc_lo, vcc_lo, 8
	s_cmp_lg_u32 vcc_lo, 0
	s_cbranch_scc0 .Lprio_skip2
	s_setprio 1
.Lprio_skip2:
.LBB0_416:
	s_add_i32 s4, s71, 2
	s_cmp_lt_i32 s4, s84
	s_cselect_b32 s4, 0, s84
	s_cselect_b32 s5, s42, s9
	s_cselect_b32 s20, s72, s43
	s_lshl_b32 s74, s4, 7
	s_sub_i32 s4, s5, s74
	s_sub_i32 s5, s20, s74
	s_add_i32 s20, s73, s5
	s_mul_i32 s5, s86, 0xc000
	s_add_i32 s74, s5, 0xffff4000
	s_add_i32 s5, s5, 0
	v_add_u32_e32 v0, s5, v192
	v_add_u32_e32 v1, s5, v193
	ds_read_b128 v[68:71], v0
	ds_read_b128 v[72:75], v1
	ds_read_b128 v[76:79], v0 offset:2048
	ds_read_b128 v[80:83], v1 offset:2048
	ds_read_b128 v[84:87], v0 offset:16384
	ds_read_b128 v[88:91], v1 offset:16384
	ds_read_b128 v[92:95], v0 offset:18432
	ds_read_b128 v[96:99], v1 offset:18432
	s_add_i32 s4, s73, s4
	s_cmp_lg_u32 s86, 0
	v_add_u32_e32 v0, s5, v190
	v_add_u32_e32 v1, s5, v191
	s_cselect_b32 s5, s74, 0x18000
	s_add_i32 s76, s83, s5
	v_lshl_add_u64 v[132:133], v[164:165], 0, s[20:21]
	s_mov_b32 m0, s76
	s_add_i32 s74, s20, s82
	s_mov_b32 s75, s21
	ds_read_b128 v[100:103], v0 offset:32768
	ds_read_b128 v[104:107], v0 offset:34816
	ds_read_b128 v[108:111], v1 offset:32768
	ds_read_b128 v[112:115], v1 offset:34816
	ds_read_b128 v[116:119], v0 offset:36864
	ds_read_b128 v[120:123], v0 offset:38912
	ds_read_b128 v[124:127], v1 offset:36864
	ds_read_b128 v[128:131], v1 offset:38912
	global_load_lds_dwordx4 v[132:133], off
	v_lshl_add_u64 v[132:133], v[164:165], 0, s[74:75]
	s_add_i32 m0, s76, 0x2000
	s_add_i32 s74, s20, s85
	global_load_lds_dwordx4 v[132:133], off
	s_add_i32 m0, s76, 0x4000
	v_lshl_add_u64 v[132:133], v[164:165], 0, s[74:75]
	s_add_i32 s20, s20, s91
	global_load_lds_dwordx4 v[132:133], off
	v_lshl_add_u64 v[132:133], v[164:165], 0, s[20:21]
	s_add_i32 m0, s76, 0x6000
	s_mov_b32 s5, s21
	global_load_lds_dwordx4 v[132:133], off
	s_add_i32 m0, s76, 0x8000
	v_lshl_add_u64 v[132:133], v[166:167], 0, s[4:5]
	s_add_i32 s20, s4, s81
	global_load_lds_dwordx4 v[132:133], off
	v_lshl_add_u64 v[132:133], v[166:167], 0, s[20:21]
	s_add_i32 m0, s76, 0xa000
	s_nop 0
	global_load_lds_dwordx4 v[132:133], off
	s_waitcnt vmcnt(6)
	s_waitcnt lgkmcnt(0)
	s_barrier
	s_waitcnt lgkmcnt(0)
	v_mfma_f32_16x16x32_bf16 v[64:67], v[68:71], v[100:103], v[64:67]
	v_mfma_f32_16x16x32_bf16 v[60:63], v[76:79], v[100:103], v[60:63]
	v_mfma_f32_16x16x32_bf16 v[56:59], v[68:71], v[104:107], v[56:59]
	v_mfma_f32_16x16x32_bf16 v[52:55], v[76:79], v[104:107], v[52:55]
	v_mfma_f32_16x16x32_bf16 v[48:51], v[68:71], v[116:119], v[48:51]
	v_mfma_f32_16x16x32_bf16 v[44:47], v[76:79], v[116:119], v[44:47]
	v_mfma_f32_16x16x32_bf16 v[40:43], v[68:71], v[120:123], v[40:43]
	v_mfma_f32_16x16x32_bf16 v[36:39], v[76:79], v[120:123], v[36:39]
	v_mfma_f32_16x16x32_bf16 v[64:67], v[72:75], v[108:111], v[64:67]
	v_mfma_f32_16x16x32_bf16 v[60:63], v[80:83], v[108:111], v[60:63]
	v_mfma_f32_16x16x32_bf16 v[56:59], v[72:75], v[112:115], v[56:59]
	v_mfma_f32_16x16x32_bf16 v[52:55], v[80:83], v[112:115], v[52:55]
	v_mfma_f32_16x16x32_bf16 v[48:51], v[72:75], v[124:127], v[48:51]
	v_mfma_f32_16x16x32_bf16 v[44:47], v[80:83], v[124:127], v[44:47]
	v_mfma_f32_16x16x32_bf16 v[40:43], v[72:75], v[128:131], v[40:43]
	v_mfma_f32_16x16x32_bf16 v[36:39], v[80:83], v[128:131], v[36:39]
	v_mfma_f32_16x16x32_bf16 v[32:35], v[84:87], v[100:103], v[32:35]
	v_mfma_f32_16x16x32_bf16 v[28:31], v[92:95], v[100:103], v[28:31]
	v_mfma_f32_16x16x32_bf16 v[24:27], v[84:87], v[104:107], v[24:27]
	v_mfma_f32_16x16x32_bf16 v[20:23], v[92:95], v[104:107], v[20:23]
	v_mfma_f32_16x16x32_bf16 v[16:19], v[84:87], v[116:119], v[16:19]
	v_mfma_f32_16x16x32_bf16 v[12:15], v[92:95], v[116:119], v[12:15]
	v_mfma_f32_16x16x32_bf16 v[8:11], v[84:87], v[120:123], v[8:11]
	v_mfma_f32_16x16x32_bf16 v[4:7], v[92:95], v[120:123], v[4:7]
	v_mfma_f32_16x16x32_bf16 v[32:35], v[88:91], v[108:111], v[32:35]
	v_mfma_f32_16x16x32_bf16 v[28:31], v[96:99], v[108:111], v[28:31]
	v_mfma_f32_16x16x32_bf16 v[24:27], v[88:91], v[112:115], v[24:27]
	v_mfma_f32_16x16x32_bf16 v[20:23], v[96:99], v[112:115], v[20:23]
	v_mfma_f32_16x16x32_bf16 v[16:19], v[88:91], v[124:127], v[16:19]
	v_mfma_f32_16x16x32_bf16 v[12:15], v[96:99], v[124:127], v[12:15]
	v_mfma_f32_16x16x32_bf16 v[8:11], v[88:91], v[128:131], v[8:11]
	v_mfma_f32_16x16x32_bf16 v[4:7], v[96:99], v[128:131], v[4:7]
	s_barrier
	s_add_i32 s4, s86, 1
	s_cmp_lg_u32 s86, 2
	s_cselect_b32 s86, s4, 0
	s_add_i32 s71, s71, 1
	s_addk_i32 s73, 0x80
	s_cmp_eq_u32 s84, s71
	s_cbranch_scc0 .LBB0_416
	s_setprio 0
	s_and_b64 vcc, exec, s[52:53]
	s_cbranch_vccz .LBB0_419

.LBB0_557:
	s_andn2_b64 vcc, exec, s[44:45]
	s_cbranch_vccnz .LBB0_560
	s_mov_b32 s9, 0
	s_movk_i32 s39, 0x100
	v_readfirstlane_b32 vcc_lo, v202
	s_nop 3
	s_lshr_b32 vcc_lo, vcc_lo, 8
	s_cmp_lg_u32 vcc_lo, 0
	s_cbranch_scc0 .Lprio_skip3
	s_setprio 1
.Lprio_skip3:
.LBB0_559:
	s_add_i32 s20, s9, 2
	s_cmp_lt_i32 s20, s54
	s_cselect_b32 s20, 0, s54
	s_cselect_b32 s41, s40, s66
	s_cselect_b32 s43, s38, s67
	s_lshl_b32 s20, s20, 7
	s_sub_i32 s41, s41, s20
	s_add_i32 s42, s39, s41
	s_mul_i32 s41, s63, 0xc000
	s_sub_i32 s20, s43, s20
	s_add_i32 s43, s41, 0xffff4000
	s_add_i32 s41, s41, 0
	v_add_u32_e32 v0, s41, v139
	v_add_u32_e32 v1, s41, v140
	ds_read_b128 v[114:117], v0
	ds_read_b128 v[118:121], v1
	ds_read_b128 v[132:135], v0 offset:2048
	ds_read_b128 v[142:145], v1 offset:2048
	ds_read_b128 v[146:149], v0 offset:16384
	ds_read_b128 v[150:153], v1 offset:16384
	ds_read_b128 v[154:157], v0 offset:18432
	ds_read_b128 v[158:161], v1 offset:18432
	s_add_i32 s20, s39, s20
	s_cmp_lg_u32 s63, 0
	v_add_u32_e32 v0, s41, v131
	v_add_u32_e32 v1, s41, v138
	s_cselect_b32 s41, s43, 0x18000
	s_add_i32 s41, s53, s41
	v_lshl_add_u64 v[4:5], v[126:127], 0, s[20:21]
	s_mov_b32 m0, s41
	s_add_i32 s48, s20, s52
	s_mov_b32 s49, s21
	ds_read_b128 v[162:165], v0 offset:32768
	ds_read_b128 v[166:169], v0 offset:34816
	ds_read_b128 v[170:173], v1 offset:32768
	ds_read_b128 v[174:177], v1 offset:34816
	ds_read_b128 v[178:181], v0 offset:36864
	ds_read_b128 v[182:185], v0 offset:38912
	ds_read_b128 v[186:189], v1 offset:36864
	ds_read_b128 v[190:193], v1 offset:38912
	global_load_lds_dwordx4 v[4:5], off
	v_lshl_add_u64 v[4:5], v[126:127], 0, s[48:49]
	s_add_i32 m0, s41, 0x2000
	s_add_i32 s48, s20, s55
	global_load_lds_dwordx4 v[4:5], off
	s_add_i32 m0, s41, 0x4000
	v_lshl_add_u64 v[4:5], v[126:127], 0, s[48:49]
	s_add_i32 s20, s20, s62
	global_load_lds_dwordx4 v[4:5], off
	v_lshl_add_u64 v[4:5], v[126:127], 0, s[20:21]
	s_add_i32 m0, s41, 0x6000
	s_mov_b32 s43, s21
	global_load_lds_dwordx4 v[4:5], off
	s_add_i32 m0, s41, 0x8000
	v_lshl_add_u64 v[4:5], v[128:129], 0, s[42:43]
	s_add_i32 s20, s42, s17
	global_load_lds_dwordx4 v[4:5], off
	v_lshl_add_u64 v[4:5], v[128:129], 0, s[20:21]
	s_add_i32 m0, s41, 0xa000
	s_nop 0
	global_load_lds_dwordx4 v[4:5], off
	s_waitcnt vmcnt(6)
	s_waitcnt lgkmcnt(0)
	s_barrier
	s_waitcnt lgkmcnt(0)
	v_mfma_f32_16x16x32_bf16 v[122:125], v[114:117], v[162:165], v[122:125]
	v_mfma_f32_16x16x32_bf16 v[54:57], v[132:135], v[162:165], v[54:57]
	v_mfma_f32_16x16x32_bf16 v[58:61], v[114:117], v[166:169], v[58:61]
	v_mfma_f32_16x16x32_bf16 v[62:65], v[132:135], v[166:169], v[62:65]
	v_mfma_f32_16x16x32_bf16 v[66:69], v[114:117], v[178:181], v[66:69]
	v_mfma_f32_16x16x32_bf16 v[70:73], v[132:135], v[178:181], v[70:73]
	v_mfma_f32_16x16x32_bf16 v[74:77], v[114:117], v[182:185], v[74:77]
	v_mfma_f32_16x16x32_bf16 v[78:81], v[132:135], v[182:185], v[78:81]
	v_mfma_f32_16x16x32_bf16 v[122:125], v[118:121], v[170:173], v[122:125]
	v_mfma_f32_16x16x32_bf16 v[54:57], v[142:145], v[170:173], v[54:57]
	v_mfma_f32_16x16x32_bf16 v[58:61], v[118:121], v[174:177], v[58:61]
	v_mfma_f32_16x16x32_bf16 v[62:65], v[142:145], v[174:177], v[62:65]
	v_mfma_f32_16x16x32_bf16 v[66:69], v[118:121], v[186:189], v[66:69]
	v_mfma_f32_16x16x32_bf16 v[70:73], v[142:145], v[186:189], v[70:73]
	v_mfma_f32_16x16x32_bf16 v[74:77], v[118:121], v[190:193], v[74:77]
	v_mfma_f32_16x16x32_bf16 v[78:81], v[142:145], v[190:193], v[78:81]
	v_mfma_f32_16x16x32_bf16 v[82:85], v[146:149], v[162:165], v[82:85]
	v_mfma_f32_16x16x32_bf16 v[86:89], v[154:157], v[162:165], v[86:89]
	v_mfma_f32_16x16x32_bf16 v[90:93], v[146:149], v[166:169], v[90:93]
	v_mfma_f32_16x16x32_bf16 v[94:97], v[154:157], v[166:169], v[94:97]
	v_mfma_f32_16x16x32_bf16 v[98:101], v[146:149], v[178:181], v[98:101]
	v_mfma_f32_16x16x32_bf16 v[102:105], v[154:157], v[178:181], v[102:105]
	v_mfma_f32_16x16x32_bf16 v[106:109], v[146:149], v[182:185], v[106:109]
	v_mfma_f32_16x16x32_bf16 v[110:113], v[154:157], v[182:185], v[110:113]
	v_mfma_f32_16x16x32_bf16 v[82:85], v[150:153], v[170:173], v[82:85]
	v_mfma_f32_16x16x32_bf16 v[86:89], v[158:161], v[170:173], v[86:89]
	v_mfma_f32_16x16x32_bf16 v[90:93], v[150:153], v[174:177], v[90:93]
	v_mfma_f32_16x16x32_bf16 v[94:97], v[158:161], v[174:177], v[94:97]
	v_mfma_f32_16x16x32_bf16 v[98:101], v[150:153], v[186:189], v[98:101]
	v_mfma_f32_16x16x32_bf16 v[102:105], v[158:161], v[186:189], v[102:105]
	v_mfma_f32_16x16x32_bf16 v[106:109], v[150:153], v[190:193], v[106:109]
	v_mfma_f32_16x16x32_bf16 v[110:113], v[158:161], v[190:193], v[110:113]
	s_barrier
	s_add_i32 s20, s63, 1
	s_cmp_lg_u32 s63, 2
	s_cselect_b32 s63, s20, 0
	s_add_i32 s9, s9, 1
	s_addk_i32 s39, 0x80
	s_cmp_eq_u32 s54, s9
	s_cbranch_scc0 .LBB0_559
	s_setprio 0

.LBB0_1274:
	v_mov_b32_e32 v131, 0
	s_andn2_b64 vcc, exec, s[8:9]
	v_mov_b32_e32 v130, v131
	v_mov_b32_e32 v129, v131
	v_mov_b32_e32 v128, v131
	v_mov_b32_e32 v127, v131
	v_mov_b32_e32 v126, v131
	v_mov_b32_e32 v125, v131
	v_mov_b32_e32 v124, v131
	v_mov_b32_e32 v115, v131
	v_mov_b32_e32 v114, v131
	v_mov_b32_e32 v113, v131
	v_mov_b32_e32 v112, v131
	v_mov_b32_e32 v111, v131
	v_mov_b32_e32 v110, v131
	v_mov_b32_e32 v109, v131
	v_mov_b32_e32 v108, v131
	v_mov_b32_e32 v99, v131
	v_mov_b32_e32 v98, v131
	v_mov_b32_e32 v97, v131
	v_mov_b32_e32 v96, v131
	v_mov_b32_e32 v95, v131
	v_mov_b32_e32 v94, v131
	v_mov_b32_e32 v93, v131
	v_mov_b32_e32 v92, v131
	v_mov_b32_e32 v83, v131
	v_mov_b32_e32 v82, v131
	v_mov_b32_e32 v81, v131
	v_mov_b32_e32 v80, v131
	v_mov_b32_e32 v79, v131
	v_mov_b32_e32 v78, v131
	v_mov_b32_e32 v77, v131
	v_mov_b32_e32 v76, v131
	v_mov_b32_e32 v123, v131
	v_mov_b32_e32 v122, v131
	v_mov_b32_e32 v121, v131
	v_mov_b32_e32 v120, v131
	v_mov_b32_e32 v119, v131
	v_mov_b32_e32 v118, v131
	v_mov_b32_e32 v117, v131
	v_mov_b32_e32 v116, v131
	v_mov_b32_e32 v107, v131
	v_mov_b32_e32 v106, v131
	v_mov_b32_e32 v105, v131
	v_mov_b32_e32 v104, v131
	v_mov_b32_e32 v103, v131
	v_mov_b32_e32 v102, v131
	v_mov_b32_e32 v101, v131
	v_mov_b32_e32 v100, v131
	v_mov_b32_e32 v91, v131
	v_mov_b32_e32 v90, v131
	v_mov_b32_e32 v89, v131
	v_mov_b32_e32 v88, v131
	v_mov_b32_e32 v87, v131
	v_mov_b32_e32 v86, v131
	v_mov_b32_e32 v85, v131
	v_mov_b32_e32 v84, v131
	v_mov_b32_e32 v75, v131
	v_mov_b32_e32 v74, v131
	v_mov_b32_e32 v73, v131
	v_mov_b32_e32 v72, v131
	v_mov_b32_e32 v71, v131
	v_mov_b32_e32 v70, v131
	v_mov_b32_e32 v69, v131
	v_mov_b32_e32 v68, v131
	v_mov_b32_e32 v67, v131
	v_mov_b32_e32 v66, v131
	v_mov_b32_e32 v65, v131
	v_mov_b32_e32 v64, v131
	v_mov_b32_e32 v63, v131
	v_mov_b32_e32 v62, v131
	v_mov_b32_e32 v61, v131
	v_mov_b32_e32 v60, v131
	v_mov_b32_e32 v51, v131
	v_mov_b32_e32 v50, v131
	v_mov_b32_e32 v49, v131
	v_mov_b32_e32 v48, v131
	v_mov_b32_e32 v47, v131
	v_mov_b32_e32 v46, v131
	v_mov_b32_e32 v45, v131
	v_mov_b32_e32 v44, v131
	v_mov_b32_e32 v35, v131
	v_mov_b32_e32 v34, v131
	v_mov_b32_e32 v33, v131
	v_mov_b32_e32 v32, v131
	v_mov_b32_e32 v31, v131
	v_mov_b32_e32 v30, v131
	v_mov_b32_e32 v29, v131
	v_mov_b32_e32 v28, v131
	v_mov_b32_e32 v19, v131
	v_mov_b32_e32 v18, v131
	v_mov_b32_e32 v17, v131
	v_mov_b32_e32 v16, v131
	v_mov_b32_e32 v15, v131
	v_mov_b32_e32 v14, v131
	v_mov_b32_e32 v13, v131
	v_mov_b32_e32 v12, v131
	v_mov_b32_e32 v59, v131
	v_mov_b32_e32 v58, v131
	v_mov_b32_e32 v57, v131
	v_mov_b32_e32 v56, v131
	v_mov_b32_e32 v55, v131
	v_mov_b32_e32 v54, v131
	v_mov_b32_e32 v53, v131
	v_mov_b32_e32 v52, v131
	v_mov_b32_e32 v43, v131
	v_mov_b32_e32 v42, v131
	v_mov_b32_e32 v41, v131
	v_mov_b32_e32 v40, v131
	v_mov_b32_e32 v39, v131
	v_mov_b32_e32 v38, v131
	v_mov_b32_e32 v37, v131
	v_mov_b32_e32 v36, v131
	v_mov_b32_e32 v27, v131
	v_mov_b32_e32 v26, v131
	v_mov_b32_e32 v25, v131
	v_mov_b32_e32 v24, v131
	v_mov_b32_e32 v23, v131
	v_mov_b32_e32 v22, v131
	v_mov_b32_e32 v21, v131
	v_mov_b32_e32 v20, v131
	v_mov_b32_e32 v11, v131
	v_mov_b32_e32 v10, v131
	v_mov_b32_e32 v9, v131
	v_mov_b32_e32 v8, v131
	v_mov_b32_e32 v7, v131
	v_mov_b32_e32 v6, v131
	v_mov_b32_e32 v5, v131
	v_mov_b32_e32 v4, v131
	s_cbranch_vccnz .LBB0_1277
	s_and_b64 s[40:41], s[74:75], exec
	v_mov_b32_e32 v4, 0
	s_cselect_b32 s45, s7, s4
	s_cselect_b32 s62, s96, s20
	s_add_i32 s63, s4, 0x80
	s_add_i32 s64, s20, 0x100
	s_mov_b32 s65, 0
	v_mov_b32_e32 v5, v4
	v_mov_b32_e32 v6, v4
	v_mov_b32_e32 v7, v4
	v_mov_b32_e32 v8, v4
	v_mov_b32_e32 v9, v4
	v_mov_b32_e32 v10, v4
	v_mov_b32_e32 v11, v4
	v_mov_b32_e32 v20, v4
	v_mov_b32_e32 v21, v4
	v_mov_b32_e32 v22, v4
	v_mov_b32_e32 v23, v4
	v_mov_b32_e32 v24, v4
	v_mov_b32_e32 v25, v4
	v_mov_b32_e32 v26, v4
	v_mov_b32_e32 v27, v4
	v_mov_b32_e32 v36, v4
	v_mov_b32_e32 v37, v4
	v_mov_b32_e32 v38, v4
	v_mov_b32_e32 v39, v4
	v_mov_b32_e32 v40, v4
	v_mov_b32_e32 v41, v4
	v_mov_b32_e32 v42, v4
	v_mov_b32_e32 v43, v4
	v_mov_b32_e32 v52, v4
	v_mov_b32_e32 v53, v4
	v_mov_b32_e32 v54, v4
	v_mov_b32_e32 v55, v4
	v_mov_b32_e32 v56, v4
	v_mov_b32_e32 v57, v4
	v_mov_b32_e32 v58, v4
	v_mov_b32_e32 v59, v4
	v_mov_b32_e32 v12, v4
	v_mov_b32_e32 v13, v4
	v_mov_b32_e32 v14, v4
	v_mov_b32_e32 v15, v4
	v_mov_b32_e32 v16, v4
	v_mov_b32_e32 v17, v4
	v_mov_b32_e32 v18, v4
	v_mov_b32_e32 v19, v4
	v_mov_b32_e32 v28, v4
	v_mov_b32_e32 v29, v4
	v_mov_b32_e32 v30, v4
	v_mov_b32_e32 v31, v4
	v_mov_b32_e32 v32, v4
	v_mov_b32_e32 v33, v4
	v_mov_b32_e32 v34, v4
	v_mov_b32_e32 v35, v4
	v_mov_b32_e32 v44, v4
	v_mov_b32_e32 v45, v4
	v_mov_b32_e32 v46, v4
	v_mov_b32_e32 v47, v4
	v_mov_b32_e32 v48, v4
	v_mov_b32_e32 v49, v4
	v_mov_b32_e32 v50, v4
	v_mov_b32_e32 v51, v4
	v_mov_b32_e32 v60, v4
	v_mov_b32_e32 v61, v4
	v_mov_b32_e32 v62, v4
	v_mov_b32_e32 v63, v4
	v_mov_b32_e32 v64, v4
	v_mov_b32_e32 v65, v4
	v_mov_b32_e32 v66, v4
	v_mov_b32_e32 v67, v4
	v_mov_b32_e32 v68, v4
	v_mov_b32_e32 v69, v4
	v_mov_b32_e32 v70, v4
	v_mov_b32_e32 v71, v4
	v_mov_b32_e32 v72, v4
	v_mov_b32_e32 v73, v4
	v_mov_b32_e32 v74, v4
	v_mov_b32_e32 v75, v4
	v_mov_b32_e32 v84, v4
	v_mov_b32_e32 v85, v4
	v_mov_b32_e32 v86, v4
	v_mov_b32_e32 v87, v4
	v_mov_b32_e32 v88, v4
	v_mov_b32_e32 v89, v4
	v_mov_b32_e32 v90, v4
	v_mov_b32_e32 v91, v4
	v_mov_b32_e32 v100, v4
	v_mov_b32_e32 v101, v4
	v_mov_b32_e32 v102, v4
	v_mov_b32_e32 v103, v4
	v_mov_b32_e32 v104, v4
	v_mov_b32_e32 v105, v4
	v_mov_b32_e32 v106, v4
	v_mov_b32_e32 v107, v4
	v_mov_b32_e32 v116, v4
	v_mov_b32_e32 v117, v4
	v_mov_b32_e32 v118, v4
	v_mov_b32_e32 v119, v4
	v_mov_b32_e32 v120, v4
	v_mov_b32_e32 v121, v4
	v_mov_b32_e32 v122, v4
	v_mov_b32_e32 v123, v4
	v_mov_b32_e32 v76, v4
	v_mov_b32_e32 v77, v4
	v_mov_b32_e32 v78, v4
	v_mov_b32_e32 v79, v4
	v_mov_b32_e32 v80, v4
	v_mov_b32_e32 v81, v4
	v_mov_b32_e32 v82, v4
	v_mov_b32_e32 v83, v4
	v_mov_b32_e32 v92, v4
	v_mov_b32_e32 v93, v4
	v_mov_b32_e32 v94, v4
	v_mov_b32_e32 v95, v4
	v_mov_b32_e32 v96, v4
	v_mov_b32_e32 v97, v4
	v_mov_b32_e32 v98, v4
	v_mov_b32_e32 v99, v4
	v_mov_b32_e32 v108, v4
	v_mov_b32_e32 v109, v4
	v_mov_b32_e32 v110, v4
	v_mov_b32_e32 v111, v4
	v_mov_b32_e32 v112, v4
	v_mov_b32_e32 v113, v4
	v_mov_b32_e32 v114, v4
	v_mov_b32_e32 v115, v4
	v_mov_b32_e32 v124, v4
	v_mov_b32_e32 v125, v4
	v_mov_b32_e32 v126, v4
	v_mov_b32_e32 v127, v4
	v_mov_b32_e32 v128, v4
	v_mov_b32_e32 v129, v4
	v_mov_b32_e32 v130, v4
	v_mov_b32_e32 v131, v4
	v_readfirstlane_b32 vcc_lo, v202
	s_nop 3
	s_lshr_b32 vcc_lo, vcc_lo, 8
	s_cmp_lg_u32 vcc_lo, 0
	s_cbranch_scc0 .Lprio_skip4
	s_setprio 1
.Lprio_skip4:
.LBB0_1276:
	s_add_i32 s4, s63, 0x80
	s_cmp_eq_u32 s94, s65
	s_cselect_b32 s42, s45, s4
	s_cselect_b32 s40, s62, s64
	s_add_i32 s5, 0, 0x10000
	v_add_u32_e32 v2, s5, v190
	v_add_u32_e32 v136, s5, v191
	ds_read_b128 v[132:135], v2
	ds_read_b128 v[136:139], v136
	v_add_u32_e32 v2, s35, v190
	v_add_u32_e32 v144, s35, v191
	s_add_i32 s43, 0, 0x14000
	ds_read_b128 v[140:143], v2
	ds_read_b128 v[144:147], v144
	v_add_u32_e32 v2, s43, v190
	v_add_u32_e32 v152, s43, v191
	ds_read_b128 v[148:151], v2
	ds_read_b128 v[152:155], v152
	v_add_u32_e32 v2, s12, v190
	v_add_u32_e32 v160, s12, v191
	ds_read_b128 v[156:159], v2
	ds_read_b128 v[160:163], v160
	s_add_i32 s4, s42, 0x80
	s_add_i32 s20, s93, s63
	v_lshl_add_u64 v[194:195], v[182:183], 0, s[20:21]
	s_add_i32 m0, s86, 0xc000
	s_add_i32 s20, s69, s63
	ds_read_b128 v[164:167], v192
	ds_read_b128 v[168:171], v192 offset:2048
	ds_read_b128 v[172:175], v193
	ds_read_b128 v[176:179], v193 offset:2048
	ds_read_b128 v[184:187], v192 offset:4096
	ds_read_b128 v[220:223], v192 offset:6144
	ds_read_b128 v[224:227], v193 offset:4096
	ds_read_b128 v[228:231], v193 offset:6144
	global_load_lds_dwordx4 v[194:195], off
	v_lshl_add_u64 v[194:195], v[182:183], 0, s[20:21]
	s_add_i32 m0, s86, 0xe000
	s_nop 0
	global_load_lds_dwordx4 v[194:195], off
	s_waitcnt vmcnt(8)
	s_waitcnt lgkmcnt(0)
	s_barrier
	s_waitcnt lgkmcnt(0)
	v_mfma_f32_16x16x32_bf16 v[128:131], v[132:135], v[164:167], v[128:131]
	v_mfma_f32_16x16x32_bf16 v[124:127], v[140:143], v[164:167], v[124:127]
	v_mfma_f32_16x16x32_bf16 v[112:115], v[132:135], v[168:171], v[112:115]
	v_mfma_f32_16x16x32_bf16 v[108:111], v[140:143], v[168:171], v[108:111]
	v_mfma_f32_16x16x32_bf16 v[96:99], v[132:135], v[184:187], v[96:99]
	v_mfma_f32_16x16x32_bf16 v[92:95], v[140:143], v[184:187], v[92:95]
	v_mfma_f32_16x16x32_bf16 v[80:83], v[132:135], v[220:223], v[80:83]
	v_mfma_f32_16x16x32_bf16 v[76:79], v[140:143], v[220:223], v[76:79]
	v_mfma_f32_16x16x32_bf16 v[128:131], v[136:139], v[172:175], v[128:131]
	v_mfma_f32_16x16x32_bf16 v[124:127], v[144:147], v[172:175], v[124:127]
	v_mfma_f32_16x16x32_bf16 v[112:115], v[136:139], v[176:179], v[112:115]
	v_mfma_f32_16x16x32_bf16 v[108:111], v[144:147], v[176:179], v[108:111]
	v_mfma_f32_16x16x32_bf16 v[96:99], v[136:139], v[224:227], v[96:99]
	v_mfma_f32_16x16x32_bf16 v[92:95], v[144:147], v[224:227], v[92:95]
	v_mfma_f32_16x16x32_bf16 v[80:83], v[136:139], v[228:231], v[80:83]
	v_mfma_f32_16x16x32_bf16 v[76:79], v[144:147], v[228:231], v[76:79]
	v_mfma_f32_16x16x32_bf16 v[120:123], v[148:151], v[164:167], v[120:123]
	v_mfma_f32_16x16x32_bf16 v[116:119], v[156:159], v[164:167], v[116:119]
	v_mfma_f32_16x16x32_bf16 v[104:107], v[148:151], v[168:171], v[104:107]
	v_mfma_f32_16x16x32_bf16 v[100:103], v[156:159], v[168:171], v[100:103]
	v_mfma_f32_16x16x32_bf16 v[88:91], v[148:151], v[184:187], v[88:91]
	v_mfma_f32_16x16x32_bf16 v[84:87], v[156:159], v[184:187], v[84:87]
	v_mfma_f32_16x16x32_bf16 v[72:75], v[148:151], v[220:223], v[72:75]
	v_mfma_f32_16x16x32_bf16 v[68:71], v[156:159], v[220:223], v[68:71]
	v_mfma_f32_16x16x32_bf16 v[120:123], v[152:155], v[172:175], v[120:123]
	v_mfma_f32_16x16x32_bf16 v[116:119], v[160:163], v[172:175], v[116:119]
	v_mfma_f32_16x16x32_bf16 v[104:107], v[152:155], v[176:179], v[104:107]
	v_mfma_f32_16x16x32_bf16 v[100:103], v[160:163], v[176:179], v[100:103]
	v_mfma_f32_16x16x32_bf16 v[88:91], v[152:155], v[224:227], v[88:91]
	v_mfma_f32_16x16x32_bf16 v[84:87], v[160:163], v[224:227], v[84:87]
	v_mfma_f32_16x16x32_bf16 v[72:75], v[152:155], v[228:231], v[72:75]
	v_mfma_f32_16x16x32_bf16 v[68:71], v[160:163], v[228:231], v[68:71]
	s_barrier
	s_mov_b32 s41, s21
	s_add_i32 s5, s5, s85
	v_lshl_add_u64 v[194:195], v[180:181], 0, s[40:41]
	s_mov_b32 m0, s5
	s_add_i32 s20, s40, s84
	ds_read_b128 v[164:167], v192 offset:16384
	ds_read_b128 v[168:171], v192 offset:18432
	ds_read_b128 v[172:175], v193 offset:16384
	ds_read_b128 v[176:179], v193 offset:18432
	ds_read_b128 v[184:187], v192 offset:20480
	ds_read_b128 v[220:223], v192 offset:22528
	ds_read_b128 v[224:227], v193 offset:20480
	ds_read_b128 v[228:231], v193 offset:22528
	global_load_lds_dwordx4 v[194:195], off
	v_lshl_add_u64 v[194:195], v[180:181], 0, s[20:21]
	s_add_i32 m0, s5, 0x2000
	s_add_i32 s20, s20, s84
	s_add_i32 s5, s43, s85
	global_load_lds_dwordx4 v[194:195], off
	v_lshl_add_u64 v[194:195], v[180:181], 0, s[20:21]
	s_mov_b32 m0, s5
	s_add_i32 s20, s20, s84
	global_load_lds_dwordx4 v[194:195], off
	v_lshl_add_u64 v[194:195], v[180:181], 0, s[20:21]
	s_add_i32 m0, s5, 0x2000
	s_mov_b32 s43, s21
	global_load_lds_dwordx4 v[194:195], off
	v_lshl_add_u64 v[194:195], v[182:183], 0, s[42:43]
	s_mov_b32 m0, s86
	s_add_i32 s20, s42, s83
	global_load_lds_dwordx4 v[194:195], off
	v_lshl_add_u64 v[194:195], v[182:183], 0, s[20:21]
	s_mov_b32 m0, s87
	s_nop 0
	global_load_lds_dwordx4 v[194:195], off
	s_waitcnt vmcnt(8)
	s_waitcnt lgkmcnt(0)
	s_barrier
	s_waitcnt lgkmcnt(0)
	v_mfma_f32_16x16x32_bf16 v[64:67], v[132:135], v[164:167], v[64:67]
	v_mfma_f32_16x16x32_bf16 v[60:63], v[140:143], v[164:167], v[60:63]
	v_mfma_f32_16x16x32_bf16 v[48:51], v[132:135], v[168:171], v[48:51]
	v_mfma_f32_16x16x32_bf16 v[44:47], v[140:143], v[168:171], v[44:47]
	v_mfma_f32_16x16x32_bf16 v[32:35], v[132:135], v[184:187], v[32:35]
	v_mfma_f32_16x16x32_bf16 v[28:31], v[140:143], v[184:187], v[28:31]
	v_mfma_f32_16x16x32_bf16 v[16:19], v[132:135], v[220:223], v[16:19]
	v_mfma_f32_16x16x32_bf16 v[12:15], v[140:143], v[220:223], v[12:15]
	v_mfma_f32_16x16x32_bf16 v[64:67], v[136:139], v[172:175], v[64:67]
	v_mfma_f32_16x16x32_bf16 v[60:63], v[144:147], v[172:175], v[60:63]
	v_mfma_f32_16x16x32_bf16 v[48:51], v[136:139], v[176:179], v[48:51]
	v_mfma_f32_16x16x32_bf16 v[44:47], v[144:147], v[176:179], v[44:47]
	v_mfma_f32_16x16x32_bf16 v[32:35], v[136:139], v[224:227], v[32:35]
	v_mfma_f32_16x16x32_bf16 v[28:31], v[144:147], v[224:227], v[28:31]
	v_mfma_f32_16x16x32_bf16 v[16:19], v[136:139], v[228:231], v[16:19]
	v_mfma_f32_16x16x32_bf16 v[12:15], v[144:147], v[228:231], v[12:15]
	v_mfma_f32_16x16x32_bf16 v[56:59], v[148:151], v[164:167], v[56:59]
	v_mfma_f32_16x16x32_bf16 v[52:55], v[156:159], v[164:167], v[52:55]
	v_mfma_f32_16x16x32_bf16 v[40:43], v[148:151], v[168:171], v[40:43]
	v_mfma_f32_16x16x32_bf16 v[36:39], v[156:159], v[168:171], v[36:39]
	v_mfma_f32_16x16x32_bf16 v[24:27], v[148:151], v[184:187], v[24:27]
	v_mfma_f32_16x16x32_bf16 v[20:23], v[156:159], v[184:187], v[20:23]
	v_mfma_f32_16x16x32_bf16 v[8:11], v[148:151], v[220:223], v[8:11]
	v_mfma_f32_16x16x32_bf16 v[4:7], v[156:159], v[220:223], v[4:7]
	v_mfma_f32_16x16x32_bf16 v[56:59], v[152:155], v[172:175], v[56:59]
	v_mfma_f32_16x16x32_bf16 v[52:55], v[160:163], v[172:175], v[52:55]
	v_mfma_f32_16x16x32_bf16 v[40:43], v[152:155], v[176:179], v[40:43]
	v_mfma_f32_16x16x32_bf16 v[36:39], v[160:163], v[176:179], v[36:39]
	v_mfma_f32_16x16x32_bf16 v[24:27], v[152:155], v[224:227], v[24:27]
	v_mfma_f32_16x16x32_bf16 v[20:23], v[160:163], v[224:227], v[20:23]
	v_mfma_f32_16x16x32_bf16 v[8:11], v[152:155], v[228:231], v[8:11]
	v_mfma_f32_16x16x32_bf16 v[4:7], v[160:163], v[228:231], v[4:7]
	s_barrier
	s_add_i32 s5, 0, 0x18000
	v_add_u32_e32 v2, s5, v190
	v_add_u32_e32 v136, s5, v191
	ds_read_b128 v[132:135], v2
	ds_read_b128 v[136:139], v136
	v_add_u32_e32 v2, s13, v190
	v_add_u32_e32 v144, s13, v191
	s_add_i32 s41, 0, 0x1c000
	ds_read_b128 v[140:143], v2
	ds_read_b128 v[144:147], v144
	v_add_u32_e32 v2, s41, v190
	v_add_u32_e32 v152, s41, v191
	ds_read_b128 v[148:151], v2
	ds_read_b128 v[152:155], v152
	v_add_u32_e32 v2, s14, v190
	v_add_u32_e32 v160, s14, v191
	ds_read_b128 v[156:159], v2
	ds_read_b128 v[160:163], v160
	s_add_i32 s20, s20, s83
	s_mov_b32 m0, s88
	v_lshl_add_u64 v[194:195], v[182:183], 0, s[20:21]
	s_add_i32 s20, s20, s83
	ds_read_b128 v[164:167], v192 offset:32768
	ds_read_b128 v[168:171], v192 offset:34816
	ds_read_b128 v[172:175], v193 offset:32768
	ds_read_b128 v[176:179], v193 offset:34816
	ds_read_b128 v[184:187], v192 offset:36864
	ds_read_b128 v[220:223], v192 offset:38912
	ds_read_b128 v[224:227], v193 offset:36864
	ds_read_b128 v[228:231], v193 offset:38912
	global_load_lds_dwordx4 v[194:195], off
	v_lshl_add_u64 v[194:195], v[182:183], 0, s[20:21]
	s_mov_b32 m0, s89
	s_nop 0
	global_load_lds_dwordx4 v[194:195], off
	s_waitcnt vmcnt(8)
	s_waitcnt lgkmcnt(0)
	s_barrier
	s_waitcnt lgkmcnt(0)
	v_mfma_f32_16x16x32_bf16 v[128:131], v[132:135], v[164:167], v[128:131]
	v_mfma_f32_16x16x32_bf16 v[124:127], v[140:143], v[164:167], v[124:127]
	v_mfma_f32_16x16x32_bf16 v[112:115], v[132:135], v[168:171], v[112:115]
	v_mfma_f32_16x16x32_bf16 v[108:111], v[140:143], v[168:171], v[108:111]
	v_mfma_f32_16x16x32_bf16 v[96:99], v[132:135], v[184:187], v[96:99]
	v_mfma_f32_16x16x32_bf16 v[92:95], v[140:143], v[184:187], v[92:95]
	v_mfma_f32_16x16x32_bf16 v[80:83], v[132:135], v[220:223], v[80:83]
	v_mfma_f32_16x16x32_bf16 v[76:79], v[140:143], v[220:223], v[76:79]
	v_mfma_f32_16x16x32_bf16 v[128:131], v[136:139], v[172:175], v[128:131]
	v_mfma_f32_16x16x32_bf16 v[124:127], v[144:147], v[172:175], v[124:127]
	v_mfma_f32_16x16x32_bf16 v[112:115], v[136:139], v[176:179], v[112:115]
	v_mfma_f32_16x16x32_bf16 v[108:111], v[144:147], v[176:179], v[108:111]
	v_mfma_f32_16x16x32_bf16 v[96:99], v[136:139], v[224:227], v[96:99]
	v_mfma_f32_16x16x32_bf16 v[92:95], v[144:147], v[224:227], v[92:95]
	v_mfma_f32_16x16x32_bf16 v[80:83], v[136:139], v[228:231], v[80:83]
	v_mfma_f32_16x16x32_bf16 v[76:79], v[144:147], v[228:231], v[76:79]
	v_mfma_f32_16x16x32_bf16 v[120:123], v[148:151], v[164:167], v[120:123]
	v_mfma_f32_16x16x32_bf16 v[116:119], v[156:159], v[164:167], v[116:119]
	v_mfma_f32_16x16x32_bf16 v[104:107], v[148:151], v[168:171], v[104:107]
	v_mfma_f32_16x16x32_bf16 v[100:103], v[156:159], v[168:171], v[100:103]
	v_mfma_f32_16x16x32_bf16 v[88:91], v[148:151], v[184:187], v[88:91]
	v_mfma_f32_16x16x32_bf16 v[84:87], v[156:159], v[184:187], v[84:87]
	v_mfma_f32_16x16x32_bf16 v[72:75], v[148:151], v[220:223], v[72:75]
	v_mfma_f32_16x16x32_bf16 v[68:71], v[156:159], v[220:223], v[68:71]
	v_mfma_f32_16x16x32_bf16 v[120:123], v[152:155], v[172:175], v[120:123]
	v_mfma_f32_16x16x32_bf16 v[116:119], v[160:163], v[172:175], v[116:119]
	v_mfma_f32_16x16x32_bf16 v[104:107], v[152:155], v[176:179], v[104:107]
	v_mfma_f32_16x16x32_bf16 v[100:103], v[160:163], v[176:179], v[100:103]
	v_mfma_f32_16x16x32_bf16 v[88:91], v[152:155], v[224:227], v[88:91]
	v_mfma_f32_16x16x32_bf16 v[84:87], v[160:163], v[224:227], v[84:87]
	v_mfma_f32_16x16x32_bf16 v[72:75], v[152:155], v[228:231], v[72:75]
	v_mfma_f32_16x16x32_bf16 v[68:71], v[160:163], v[228:231], v[68:71]
	s_barrier
	s_add_i32 s20, s40, 0x80
	s_add_i32 s5, s5, s85
	v_lshl_add_u64 v[194:195], v[180:181], 0, s[20:21]
	s_mov_b32 m0, s5
	s_add_i32 s20, s20, s84
	ds_read_b128 v[164:167], v192 offset:49152
	ds_read_b128 v[168:171], v192 offset:51200
	ds_read_b128 v[172:175], v193 offset:49152
	ds_read_b128 v[176:179], v193 offset:51200
	ds_read_b128 v[184:187], v192 offset:53248
	ds_read_b128 v[220:223], v192 offset:55296
	ds_read_b128 v[224:227], v193 offset:53248
	ds_read_b128 v[228:231], v193 offset:55296
	global_load_lds_dwordx4 v[194:195], off
	v_lshl_add_u64 v[194:195], v[180:181], 0, s[20:21]
	s_add_i32 m0, s5, 0x2000
	s_add_i32 s20, s20, s84
	s_add_i32 s5, s41, s85
	global_load_lds_dwordx4 v[194:195], off
	v_lshl_add_u64 v[194:195], v[180:181], 0, s[20:21]
	s_mov_b32 m0, s5
	s_add_i32 s20, s20, s84
	global_load_lds_dwordx4 v[194:195], off
	v_lshl_add_u64 v[194:195], v[180:181], 0, s[20:21]
	s_add_i32 m0, s5, 0x2000
	s_mov_b32 s5, s21
	global_load_lds_dwordx4 v[194:195], off
	v_lshl_add_u64 v[194:195], v[182:183], 0, s[4:5]
	s_mov_b32 m0, s90
	s_add_i32 s20, s4, s83
	global_load_lds_dwordx4 v[194:195], off
	v_lshl_add_u64 v[194:195], v[182:183], 0, s[20:21]
	s_mov_b32 m0, s91
	s_nop 0
	global_load_lds_dwordx4 v[194:195], off
	s_waitcnt vmcnt(8)
	s_waitcnt lgkmcnt(0)
	s_barrier
	s_waitcnt lgkmcnt(0)
	v_mfma_f32_16x16x32_bf16 v[64:67], v[132:135], v[164:167], v[64:67]
	v_mfma_f32_16x16x32_bf16 v[60:63], v[140:143], v[164:167], v[60:63]
	v_mfma_f32_16x16x32_bf16 v[48:51], v[132:135], v[168:171], v[48:51]
	v_mfma_f32_16x16x32_bf16 v[44:47], v[140:143], v[168:171], v[44:47]
	v_mfma_f32_16x16x32_bf16 v[32:35], v[132:135], v[184:187], v[32:35]
	v_mfma_f32_16x16x32_bf16 v[28:31], v[140:143], v[184:187], v[28:31]
	v_mfma_f32_16x16x32_bf16 v[16:19], v[132:135], v[220:223], v[16:19]
	v_mfma_f32_16x16x32_bf16 v[12:15], v[140:143], v[220:223], v[12:15]
	v_mfma_f32_16x16x32_bf16 v[64:67], v[136:139], v[172:175], v[64:67]
	v_mfma_f32_16x16x32_bf16 v[60:63], v[144:147], v[172:175], v[60:63]
	v_mfma_f32_16x16x32_bf16 v[48:51], v[136:139], v[176:179], v[48:51]
	v_mfma_f32_16x16x32_bf16 v[44:47], v[144:147], v[176:179], v[44:47]
	v_mfma_f32_16x16x32_bf16 v[32:35], v[136:139], v[224:227], v[32:35]
	v_mfma_f32_16x16x32_bf16 v[28:31], v[144:147], v[224:227], v[28:31]
	v_mfma_f32_16x16x32_bf16 v[16:19], v[136:139], v[228:231], v[16:19]
	v_mfma_f32_16x16x32_bf16 v[12:15], v[144:147], v[228:231], v[12:15]
	v_mfma_f32_16x16x32_bf16 v[56:59], v[148:151], v[164:167], v[56:59]
	v_mfma_f32_16x16x32_bf16 v[52:55], v[156:159], v[164:167], v[52:55]
	v_mfma_f32_16x16x32_bf16 v[40:43], v[148:151], v[168:171], v[40:43]
	v_mfma_f32_16x16x32_bf16 v[36:39], v[156:159], v[168:171], v[36:39]
	v_mfma_f32_16x16x32_bf16 v[24:27], v[148:151], v[184:187], v[24:27]
	v_mfma_f32_16x16x32_bf16 v[20:23], v[156:159], v[184:187], v[20:23]
	v_mfma_f32_16x16x32_bf16 v[8:11], v[148:151], v[220:223], v[8:11]
	v_mfma_f32_16x16x32_bf16 v[4:7], v[156:159], v[220:223], v[4:7]
	v_mfma_f32_16x16x32_bf16 v[56:59], v[152:155], v[172:175], v[56:59]
	v_mfma_f32_16x16x32_bf16 v[52:55], v[160:163], v[172:175], v[52:55]
	v_mfma_f32_16x16x32_bf16 v[40:43], v[152:155], v[176:179], v[40:43]
	v_mfma_f32_16x16x32_bf16 v[36:39], v[160:163], v[176:179], v[36:39]
	v_mfma_f32_16x16x32_bf16 v[24:27], v[152:155], v[224:227], v[24:27]
	v_mfma_f32_16x16x32_bf16 v[20:23], v[160:163], v[224:227], v[20:23]
	v_mfma_f32_16x16x32_bf16 v[8:11], v[152:155], v[228:231], v[8:11]
	v_mfma_f32_16x16x32_bf16 v[4:7], v[160:163], v[228:231], v[4:7]
	s_barrier
	s_add_i32 s65, s65, 2
	s_addk_i32 s63, 0x100
	s_addk_i32 s64, 0x100
	s_cmp_ge_i32 s65, s92
	s_cbranch_scc0 .LBB0_1276
	s_setprio 0
